# P3 main loop: f32 row-sum wave all-reduce with DPP rotations and permlane swaps instead of six ds_bpermute round trips
# baseline (speedup 1.0000x reference)
; __device__ __forceinline__ void p3_dots(const u32x2 (&ur)[4], const unsigned* rec, int lane, int (&pt)[4]) {
;     const u32x4 qh = *(const u32x4*)(rec + 256 + lane * 4);
; #pragma unroll
;     for (int u = 0; u < 4; u++) {
;         const int w0 = (int)ur[u].x, w1 = (int)ur[u].y;
;         int dh = __builtin_amdgcn_sdot8(w0, (int)qh.x, 0, false);
;         dh = __builtin_amdgcn_sdot8(w1, (int)qh.z, dh, false);
;         int dl = __builtin_amdgcn_sdot8(w0, (int)qh.y, 0, false);
;         dl = __builtin_amdgcn_sdot8(w1, (int)qh.w, dl, false);
;         pt[u] = (dh << 4) + dl;
;     }
; }
; template <int CTRL> __device__ __forceinline__ int dpp_i(int v) { return __builtin_amdgcn_mov_dpp(v, CTRL, 0xF, 0xF, true); }
; __device__ __forceinline__ int xrow_sum_i(int v) {
;     const auto a = __builtin_amdgcn_permlane16_swap((unsigned)v, (unsigned)v, false, false);
;     v = (int)a[0] + (int)a[1];
;     const auto b = __builtin_amdgcn_permlane32_swap((unsigned)v, (unsigned)v, false, false);
;     return (int)b[0] + (int)b[1];
; }
; __device__ __forceinline__ float p3_weight(const int (&pt)[4], int lane, float sh, int hs8, const P3Sc& sc) {
;     int m2[2], m1;
;     const bool c0 = lane & 1;
; #pragma unroll
;     for (int j = 0; j < 2; j++) { const int keep = c0 ? pt[j + 2] : pt[j], send = c0 ? pt[j] : pt[j + 2]; m2[j] = keep + dpp_i<0xB1>(send); }
;     const bool c1 = lane & 2;
;     { const int keep = c1 ? m2[1] : m2[0], send = c1 ? m2[0] : m2[1]; m1 = keep + dpp_i<0x4E>(send); }
;     m1 += dpp_i<0x124>(m1);
;     m1 += dpp_i<0x128>(m1);
;     m1 = xrow_sum_i(m1);
;     const float aval = (float)(m1 - hs8) * sc.su;
;     return sc.gm * gelu_erf(aval);
; }
; __device__ __forceinline__ void p3_axpy(const u32x2 (&vr)[4], float ws, f32x2 (&acc)[8]) {
; #pragma unroll
;     for (int u = 0; u < 4; u++) {
;         const int la = ((u >> 1) & 1) | ((u & 1) << 1);
;         const float wu = __builtin_bit_cast(float, __builtin_amdgcn_readlane(__builtin_bit_cast(int, ws), la));
;         const f32x2 w2 = {wu, wu};
;         const unsigned vw[2] = {vr[u].x, vr[u].y};
; #pragma unroll
;         for (int i = 0; i < 2; i++) {
;             acc[i * 4 + 0] = __builtin_elementwise_fma(w2, __builtin_amdgcn_cvt_scalef32_pk_f32_fp4(vw[i], 1.0f, 0), acc[i * 4 + 0]);
.LBB0_1075:
	v_add_u32_e32 v134, s5, v121
	v_add_u32_e32 v135, s5, v137
	ds_read_b128 v[140:143], v134
	ds_read_b128 v[144:147], v134 offset:2560
	s_waitcnt vmcnt(12) lgkmcnt(2)
	v_dot8_i32_i4 v12, v80, v4, 0
	v_dot8_i32_i4 v27, v80, v5, 0
	v_dot8_i32_i4 v131, v74, v4, 0
	v_dot8_i32_i4 v132, v74, v5, 0
	v_dot8c_i32_i4_e32 v12, v81, v6
	v_dot8c_i32_i4_e32 v27, v81, v7
	v_dot8c_i32_i4_e32 v131, v75, v6
	v_dot8c_i32_i4_e32 v132, v75, v7
	v_dot8_i32_i4 v133, v84, v4, 0
	v_dot8_i32_i4 v176, v84, v5, 0
	v_dot8_i32_i4 v177, v82, v4, 0
	v_dot8_i32_i4 v178, v82, v5, 0
	v_dot8c_i32_i4_e32 v133, v85, v6
	v_dot8c_i32_i4_e32 v176, v85, v7
	v_dot8c_i32_i4_e32 v177, v83, v6
	v_dot8c_i32_i4_e32 v178, v83, v7
	v_lshl_add_u32 v27, v12, 4, v27
	v_lshl_add_u32 v131, v131, 4, v132
	v_lshl_add_u32 v132, v133, 4, v176
	v_lshl_add_u32 v133, v177, 4, v178
	v_cndmask_b32_e64 v12, v132, v27, s[0:1]
	v_cndmask_b32_e64 v27, v27, v132, s[0:1]
	s_waitcnt lgkmcnt(0)
	v_lshl_add_u32 v140, v140, 9, v136
	v_add_u32_dpp v12, v27, v12 quad_perm:[1,0,3,2] row_mask:0xf bank_mask:0xf bound_ctrl:1
	v_cndmask_b32_e64 v27, v133, v131, s[0:1]
	v_cndmask_b32_e64 v131, v131, v133, s[0:1]
	v_lshl_add_u32 v141, v141, 9, v136
	v_lshl_add_u32 v142, v142, 9, v136
	v_add_u32_dpp v27, v131, v27 quad_perm:[1,0,3,2] row_mask:0xf bank_mask:0xf bound_ctrl:1
	v_cndmask_b32_e64 v131, v27, v12, s[2:3]
	v_cndmask_b32_e64 v12, v12, v27, s[2:3]
	v_lshl_add_u32 v143, v143, 9, v136
	global_load_dwordx2 v[80:81], v140, s[50:51]
	v_add_u32_dpp v12, v12, v131 quad_perm:[2,3,0,1] row_mask:0xf bank_mask:0xf bound_ctrl:1
	global_load_dwordx2 v[74:75], v141, s[50:51]
	global_load_dwordx2 v[84:85], v142, s[50:51]
	v_add_u32_dpp v12, v12, v12 row_ror:4 row_mask:0xf bank_mask:0xf bound_ctrl:1
	global_load_dwordx2 v[82:83], v143, s[50:51]
	s_waitcnt vmcnt(8)
	v_add_u32_dpp v181, v12, v12 row_ror:8 row_mask:0xf bank_mask:0xf bound_ctrl:1
	v_dot8_i32_i4 v12, v66, v0, 0
	v_dot8_i32_i4 v27, v66, v1, 0
	v_dot8_i32_i4 v131, v60, v0, 0
	v_dot8_i32_i4 v132, v60, v1, 0
	v_dot8c_i32_i4_e32 v12, v67, v2
	v_dot8c_i32_i4_e32 v27, v67, v3
	v_dot8c_i32_i4_e32 v131, v61, v2
	v_dot8c_i32_i4_e32 v132, v61, v3
	v_dot8_i32_i4 v133, v68, v0, 0
	v_dot8_i32_i4 v176, v68, v1, 0
	v_dot8_i32_i4 v177, v64, v0, 0
	v_dot8_i32_i4 v178, v64, v1, 0
	v_dot8c_i32_i4_e32 v133, v69, v2
	v_dot8c_i32_i4_e32 v176, v69, v3
	v_dot8c_i32_i4_e32 v177, v65, v2
	v_dot8c_i32_i4_e32 v178, v65, v3
	v_lshl_add_u32 v27, v12, 4, v27
	v_lshl_add_u32 v131, v131, 4, v132
	v_lshl_add_u32 v132, v133, 4, v176
	v_lshl_add_u32 v133, v177, 4, v178
	v_cndmask_b32_e64 v12, v132, v27, s[0:1]
	v_cndmask_b32_e64 v27, v27, v132, s[0:1]
	v_lshl_add_u32 v144, v144, 9, v136
	v_lshl_add_u32 v145, v145, 9, v136
	v_add_u32_dpp v12, v27, v12 quad_perm:[1,0,3,2] row_mask:0xf bank_mask:0xf bound_ctrl:1
	v_cndmask_b32_e64 v27, v133, v131, s[0:1]
	v_cndmask_b32_e64 v131, v131, v133, s[0:1]
	v_lshl_add_u32 v146, v146, 9, v136
	v_lshl_add_u32 v147, v147, 9, v136
	v_add_u32_dpp v27, v131, v27 quad_perm:[1,0,3,2] row_mask:0xf bank_mask:0xf bound_ctrl:1
	v_cndmask_b32_e64 v131, v27, v12, s[2:3]
	v_cndmask_b32_e64 v12, v12, v27, s[2:3]
	global_load_dwordx2 v[66:67], v144, s[50:51]
	global_load_dwordx2 v[60:61], v145, s[50:51]
	v_add_u32_dpp v12, v12, v131 quad_perm:[2,3,0,1] row_mask:0xf bank_mask:0xf bound_ctrl:1
	global_load_dwordx2 v[68:69], v146, s[50:51]
	global_load_dwordx2 v[64:65], v147, s[50:51]
	v_add_u32_dpp v12, v12, v12 row_ror:4 row_mask:0xf bank_mask:0xf bound_ctrl:1
	v_cvt_scalef32_pk_f32_fp4 v[160:161], v72, 1.0
	v_cvt_scalef32_pk_f32_fp4 v[162:163], v72, 1.0 op_sel:[1,0,0]
	v_add_u32_dpp v12, v12, v12 row_ror:8 row_mask:0xf bank_mask:0xf bound_ctrl:1
	v_cvt_scalef32_pk_f32_fp4 v[164:165], v72, 1.0 op_sel:[0,1,0]
	v_cvt_scalef32_pk_f32_fp4 v[166:167], v72, 1.0 op_sel:[1,1,0]
	v_permlane16_swap_b32_e32 v181, v12
	v_add_u32_e32 v12, v181, v12
	v_mov_b32_e32 v27, v12
	v_cvt_scalef32_pk_f32_fp4 v[168:169], v73, 1.0
	v_cvt_scalef32_pk_f32_fp4 v[170:171], v73, 1.0 op_sel:[1,0,0]
	v_permlane32_swap_b32_e32 v12, v27
	v_add_u32_e32 v12, v27, v12
	v_cvt_f32_i32_e32 v12, v12
	v_mul_f32_e32 v12, v77, v12
	v_fma_f32 v179, |v12|, s39, 1.0
	v_rcp_f32_e32 v179, v179
	v_cmp_gt_f32_e32 vcc, 0, v12
	v_fmamk_f32 v180, v179, 0x3f07dc22, v129
	v_fmaak_f32 v180, v179, v180, 0x3f35f0e3
	v_fmaak_f32 v180, v179, v180, 0xbe11a98e
	v_fmaak_f32 v180, v179, v180, 0x3e027906
	v_mul_f32_e32 v179, v179, v180
	v_mul_f32_e32 v180, v12, v12
	v_mul_f32_e32 v180, 0xbf38aa3b, v180
	v_exp_f32_e32 v180, v180
	v_cvt_scalef32_pk_f32_fp4 v[172:173], v73, 1.0 op_sel:[0,1,0]
	v_mul_f32_e32 v179, v180, v179
	v_mul_f32_e32 v180, v12, v179
	v_fma_f32 v12, -v12, v179, v12
	v_cndmask_b32_e32 v12, v12, v180, vcc
	v_mul_f32_e32 v12, v76, v12
	ds_read2st64_b32 v[76:77], v135 offset1:6
	v_readlane_b32 s4, v12, 0
	v_cvt_scalef32_pk_f32_fp4 v[174:175], v73, 1.0 op_sel:[1,1,0]
	global_load_dwordx2 v[72:73], v140, s[52:53]
	v_pk_fma_f32 v[100:101], s[4:5], v[160:161], v[100:101] op_sel_hi:[0,1,1]
	v_pk_fma_f32 v[98:99], s[4:5], v[162:163], v[98:99] op_sel_hi:[0,1,1]
	v_pk_fma_f32 v[96:97], s[4:5], v[164:165], v[96:97] op_sel_hi:[0,1,1]
	v_pk_fma_f32 v[94:95], s[4:5], v[166:167], v[94:95] op_sel_hi:[0,1,1]
	v_pk_fma_f32 v[92:93], s[4:5], v[168:169], v[92:93] op_sel_hi:[0,1,1]
	v_pk_fma_f32 v[90:91], s[4:5], v[170:171], v[90:91] op_sel_hi:[0,1,1]
	v_pk_fma_f32 v[88:89], s[4:5], v[172:173], v[88:89] op_sel_hi:[0,1,1]
	v_pk_fma_f32 v[86:87], s[4:5], v[174:175], v[86:87] op_sel_hi:[0,1,1]
	v_readlane_b32 s4, v12, 2
	v_cvt_scalef32_pk_f32_fp4 v[160:161], v70, 1.0
	v_cvt_scalef32_pk_f32_fp4 v[162:163], v70, 1.0 op_sel:[1,0,0]
; __device__ __forceinline__ void p3_axpy(const u32x2 (&vr)[4], float ws, f32x2 (&acc)[8]) {
; #pragma unroll
;     for (int u = 0; u < 4; u++) {
;         const int la = ((u >> 1) & 1) | ((u & 1) << 1);
;         const float wu = __builtin_bit_cast(float, __builtin_amdgcn_readlane(__builtin_bit_cast(int, ws), la));
;         const f32x2 w2 = {wu, wu};
;         const unsigned vw[2] = {vr[u].x, vr[u].y};
; #pragma unroll
;         for (int i = 0; i < 2; i++) {
;             acc[i * 4 + 0] = __builtin_elementwise_fma(w2, __builtin_amdgcn_cvt_scalef32_pk_f32_fp4(vw[i], 1.0f, 0), acc[i * 4 + 0]);
;             acc[i * 4 + 1] = __builtin_elementwise_fma(w2, __builtin_amdgcn_cvt_scalef32_pk_f32_fp4(vw[i], 1.0f, 1), acc[i * 4 + 1]);
;             acc[i * 4 + 2] = __builtin_elementwise_fma(w2, __builtin_amdgcn_cvt_scalef32_pk_f32_fp4(vw[i], 1.0f, 2), acc[i * 4 + 2]);
;             acc[i * 4 + 3] = __builtin_elementwise_fma(w2, __builtin_amdgcn_cvt_scalef32_pk_f32_fp4(vw[i], 1.0f, 3), acc[i * 4 + 3]);
;         }
;     }
; }
	v_pk_fma_f32 v[100:101], s[4:5], v[160:161], v[100:101] op_sel_hi:[0,1,1]
	v_cvt_scalef32_pk_f32_fp4 v[164:165], v70, 1.0 op_sel:[0,1,0]
	v_pk_fma_f32 v[98:99], s[4:5], v[162:163], v[98:99] op_sel_hi:[0,1,1]
	v_cvt_scalef32_pk_f32_fp4 v[166:167], v70, 1.0 op_sel:[1,1,0]
	v_pk_fma_f32 v[96:97], s[4:5], v[164:165], v[96:97] op_sel_hi:[0,1,1]
	v_cvt_scalef32_pk_f32_fp4 v[168:169], v71, 1.0
	v_pk_fma_f32 v[94:95], s[4:5], v[166:167], v[94:95] op_sel_hi:[0,1,1]
	v_cvt_scalef32_pk_f32_fp4 v[170:171], v71, 1.0 op_sel:[1,0,0]
	v_pk_fma_f32 v[92:93], s[4:5], v[168:169], v[92:93] op_sel_hi:[0,1,1]
	v_cvt_scalef32_pk_f32_fp4 v[172:173], v71, 1.0 op_sel:[0,1,0]
	v_pk_fma_f32 v[90:91], s[4:5], v[170:171], v[90:91] op_sel_hi:[0,1,1]
	v_cvt_scalef32_pk_f32_fp4 v[174:175], v71, 1.0 op_sel:[1,1,0]
	v_pk_fma_f32 v[88:89], s[4:5], v[172:173], v[88:89] op_sel_hi:[0,1,1]
	v_pk_fma_f32 v[86:87], s[4:5], v[174:175], v[86:87] op_sel_hi:[0,1,1]
	global_load_dwordx2 v[70:71], v141, s[52:53]
	v_readlane_b32 s4, v12, 1
	v_cvt_scalef32_pk_f32_fp4 v[160:161], v62, 1.0
	v_cvt_scalef32_pk_f32_fp4 v[162:163], v62, 1.0 op_sel:[1,0,0]
	v_pk_fma_f32 v[100:101], s[4:5], v[160:161], v[100:101] op_sel_hi:[0,1,1]
	v_cvt_scalef32_pk_f32_fp4 v[164:165], v62, 1.0 op_sel:[0,1,0]
	v_pk_fma_f32 v[98:99], s[4:5], v[162:163], v[98:99] op_sel_hi:[0,1,1]
	v_cvt_scalef32_pk_f32_fp4 v[166:167], v62, 1.0 op_sel:[1,1,0]
	v_pk_fma_f32 v[96:97], s[4:5], v[164:165], v[96:97] op_sel_hi:[0,1,1]
	v_cvt_scalef32_pk_f32_fp4 v[168:169], v63, 1.0
	v_pk_fma_f32 v[94:95], s[4:5], v[166:167], v[94:95] op_sel_hi:[0,1,1]
	v_cvt_scalef32_pk_f32_fp4 v[170:171], v63, 1.0 op_sel:[1,0,0]
	v_pk_fma_f32 v[92:93], s[4:5], v[168:169], v[92:93] op_sel_hi:[0,1,1]
	v_cvt_scalef32_pk_f32_fp4 v[172:173], v63, 1.0 op_sel:[0,1,0]
	v_pk_fma_f32 v[90:91], s[4:5], v[170:171], v[90:91] op_sel_hi:[0,1,1]
	v_cvt_scalef32_pk_f32_fp4 v[174:175], v63, 1.0 op_sel:[1,1,0]
	v_pk_fma_f32 v[88:89], s[4:5], v[172:173], v[88:89] op_sel_hi:[0,1,1]
	v_pk_fma_f32 v[86:87], s[4:5], v[174:175], v[86:87] op_sel_hi:[0,1,1]
	global_load_dwordx2 v[62:63], v142, s[52:53]
	v_readlane_b32 s4, v12, 3
	v_cvt_scalef32_pk_f32_fp4 v[160:161], v58, 1.0
	v_cvt_scalef32_pk_f32_fp4 v[162:163], v58, 1.0 op_sel:[1,0,0]
	v_pk_fma_f32 v[100:101], s[4:5], v[160:161], v[100:101] op_sel_hi:[0,1,1]
	v_cvt_scalef32_pk_f32_fp4 v[164:165], v58, 1.0 op_sel:[0,1,0]
	v_pk_fma_f32 v[98:99], s[4:5], v[162:163], v[98:99] op_sel_hi:[0,1,1]
	v_cvt_scalef32_pk_f32_fp4 v[166:167], v58, 1.0 op_sel:[1,1,0]
	v_pk_fma_f32 v[96:97], s[4:5], v[164:165], v[96:97] op_sel_hi:[0,1,1]
	v_cvt_scalef32_pk_f32_fp4 v[168:169], v59, 1.0
	v_pk_fma_f32 v[94:95], s[4:5], v[166:167], v[94:95] op_sel_hi:[0,1,1]
	v_cvt_scalef32_pk_f32_fp4 v[170:171], v59, 1.0 op_sel:[1,0,0]
	v_pk_fma_f32 v[92:93], s[4:5], v[168:169], v[92:93] op_sel_hi:[0,1,1]
	v_cvt_scalef32_pk_f32_fp4 v[172:173], v59, 1.0 op_sel:[0,1,0]
	v_pk_fma_f32 v[90:91], s[4:5], v[170:171], v[90:91] op_sel_hi:[0,1,1]
	v_cvt_scalef32_pk_f32_fp4 v[174:175], v59, 1.0 op_sel:[1,1,0]
	v_pk_fma_f32 v[88:89], s[4:5], v[172:173], v[88:89] op_sel_hi:[0,1,1]
	v_pk_fma_f32 v[86:87], s[4:5], v[174:175], v[86:87] op_sel_hi:[0,1,1]
	global_load_dwordx2 v[58:59], v143, s[52:53]
	s_waitcnt vmcnt(15)
	v_readlane_b32 s4, v12, 16
	v_cvt_scalef32_pk_f32_fp4 v[160:161], v40, 1.0
	v_cvt_scalef32_pk_f32_fp4 v[162:163], v40, 1.0 op_sel:[1,0,0]
	v_pk_fma_f32 v[52:53], s[4:5], v[160:161], v[52:53] op_sel_hi:[0,1,1]
	v_cvt_scalef32_pk_f32_fp4 v[164:165], v40, 1.0 op_sel:[0,1,0]
	v_pk_fma_f32 v[50:51], s[4:5], v[162:163], v[50:51] op_sel_hi:[0,1,1]
	v_cvt_scalef32_pk_f32_fp4 v[166:167], v40, 1.0 op_sel:[1,1,0]
	v_pk_fma_f32 v[48:49], s[4:5], v[164:165], v[48:49] op_sel_hi:[0,1,1]
	v_cvt_scalef32_pk_f32_fp4 v[168:169], v41, 1.0
	v_pk_fma_f32 v[46:47], s[4:5], v[166:167], v[46:47] op_sel_hi:[0,1,1]
	v_cvt_scalef32_pk_f32_fp4 v[170:171], v41, 1.0 op_sel:[1,0,0]
	v_pk_fma_f32 v[44:45], s[4:5], v[168:169], v[44:45] op_sel_hi:[0,1,1]
	v_cvt_scalef32_pk_f32_fp4 v[172:173], v41, 1.0 op_sel:[0,1,0]
	v_pk_fma_f32 v[42:43], s[4:5], v[170:171], v[42:43] op_sel_hi:[0,1,1]
	v_cvt_scalef32_pk_f32_fp4 v[174:175], v41, 1.0 op_sel:[1,1,0]
	v_pk_fma_f32 v[54:55], s[4:5], v[172:173], v[54:55] op_sel_hi:[0,1,1]
	v_pk_fma_f32 v[56:57], s[4:5], v[174:175], v[56:57] op_sel_hi:[0,1,1]
	global_load_dwordx2 v[40:41], v144, s[52:53]
	s_waitcnt vmcnt(15)
	v_readlane_b32 s4, v12, 18
	v_cvt_scalef32_pk_f32_fp4 v[160:161], v38, 1.0
	v_cvt_scalef32_pk_f32_fp4 v[162:163], v38, 1.0 op_sel:[1,0,0]
	v_pk_fma_f32 v[52:53], s[4:5], v[160:161], v[52:53] op_sel_hi:[0,1,1]
	v_cvt_scalef32_pk_f32_fp4 v[164:165], v38, 1.0 op_sel:[0,1,0]
	v_pk_fma_f32 v[50:51], s[4:5], v[162:163], v[50:51] op_sel_hi:[0,1,1]
	v_cvt_scalef32_pk_f32_fp4 v[166:167], v38, 1.0 op_sel:[1,1,0]
	v_pk_fma_f32 v[48:49], s[4:5], v[164:165], v[48:49] op_sel_hi:[0,1,1]
	v_cvt_scalef32_pk_f32_fp4 v[168:169], v39, 1.0
	v_pk_fma_f32 v[46:47], s[4:5], v[166:167], v[46:47] op_sel_hi:[0,1,1]
	v_cvt_scalef32_pk_f32_fp4 v[170:171], v39, 1.0 op_sel:[1,0,0]
	v_pk_fma_f32 v[44:45], s[4:5], v[168:169], v[44:45] op_sel_hi:[0,1,1]
	v_cvt_scalef32_pk_f32_fp4 v[172:173], v39, 1.0 op_sel:[0,1,0]
	v_pk_fma_f32 v[42:43], s[4:5], v[170:171], v[42:43] op_sel_hi:[0,1,1]
	v_cvt_scalef32_pk_f32_fp4 v[174:175], v39, 1.0 op_sel:[1,1,0]
	v_pk_fma_f32 v[54:55], s[4:5], v[172:173], v[54:55] op_sel_hi:[0,1,1]
	v_pk_fma_f32 v[56:57], s[4:5], v[174:175], v[56:57] op_sel_hi:[0,1,1]
	global_load_dwordx2 v[38:39], v145, s[52:53]
	s_waitcnt vmcnt(15)
; __device__ __forceinline__ void p3_dots(const u32x2 (&ur)[4], const unsigned* rec, int lane, int (&pt)[4]) {
;     const u32x4 qh = *(const u32x4*)(rec + 256 + lane * 4);
; #pragma unroll
;     for (int u = 0; u < 4; u++) {
;         const int w0 = (int)ur[u].x, w1 = (int)ur[u].y;
;         int dh = __builtin_amdgcn_sdot8(w0, (int)qh.x, 0, false);
;         dh = __builtin_amdgcn_sdot8(w1, (int)qh.z, dh, false);
;         int dl = __builtin_amdgcn_sdot8(w0, (int)qh.y, 0, false);
;         dl = __builtin_amdgcn_sdot8(w1, (int)qh.w, dl, false);
;         pt[u] = (dh << 4) + dl;
;     }
; }
; template <int CTRL> __device__ __forceinline__ int dpp_i(int v) { return __builtin_amdgcn_mov_dpp(v, CTRL, 0xF, 0xF, true); }
; __device__ __forceinline__ int xrow_sum_i(int v) {
;     const auto a = __builtin_amdgcn_permlane16_swap((unsigned)v, (unsigned)v, false, false);
;     v = (int)a[0] + (int)a[1];
;     const auto b = __builtin_amdgcn_permlane32_swap((unsigned)v, (unsigned)v, false, false);
;     return (int)b[0] + (int)b[1];
; }
; __device__ __forceinline__ float p3_weight(const int (&pt)[4], int lane, float sh, int hs8, const P3Sc& sc) {
;     int m2[2], m1;
;     const bool c0 = lane & 1;
; #pragma unroll
;     for (int j = 0; j < 2; j++) { const int keep = c0 ? pt[j + 2] : pt[j], send = c0 ? pt[j] : pt[j + 2]; m2[j] = keep + dpp_i<0xB1>(send); }
;     const bool c1 = lane & 2;
;     { const int keep = c1 ? m2[1] : m2[0], send = c1 ? m2[0] : m2[1]; m1 = keep + dpp_i<0x4E>(send); }
;     m1 += dpp_i<0x124>(m1);
;     m1 += dpp_i<0x128>(m1);
;     m1 = xrow_sum_i(m1);
;     const float aval = (float)(m1 - hs8) * sc.su;
;     return sc.gm * gelu_erf(aval);
; }
; __device__ __forceinline__ void p3_axpy(const u32x2 (&vr)[4], float ws, f32x2 (&acc)[8]) {
; #pragma unroll
;     for (int u = 0; u < 4; u++) {
;         const int la = ((u >> 1) & 1) | ((u & 1) << 1);
;         const float wu = __builtin_bit_cast(float, __builtin_amdgcn_readlane(__builtin_bit_cast(int, ws), la));
;         const f32x2 w2 = {wu, wu};
;         const unsigned vw[2] = {vr[u].x, vr[u].y};
; #pragma unroll
;         for (int i = 0; i < 2; i++) {
;             acc[i * 4 + 0] = __builtin_elementwise_fma(w2, __builtin_amdgcn_cvt_scalef32_pk_f32_fp4(vw[i], 1.0f, 0), acc[i * 4 + 0]);
	v_readlane_b32 s4, v12, 17
	v_cvt_scalef32_pk_f32_fp4 v[160:161], v36, 1.0
	v_cvt_scalef32_pk_f32_fp4 v[162:163], v36, 1.0 op_sel:[1,0,0]
	v_pk_fma_f32 v[52:53], s[4:5], v[160:161], v[52:53] op_sel_hi:[0,1,1]
	v_cvt_scalef32_pk_f32_fp4 v[164:165], v36, 1.0 op_sel:[0,1,0]
	v_pk_fma_f32 v[50:51], s[4:5], v[162:163], v[50:51] op_sel_hi:[0,1,1]
	v_cvt_scalef32_pk_f32_fp4 v[166:167], v36, 1.0 op_sel:[1,1,0]
	v_pk_fma_f32 v[48:49], s[4:5], v[164:165], v[48:49] op_sel_hi:[0,1,1]
	v_cvt_scalef32_pk_f32_fp4 v[168:169], v37, 1.0
	v_pk_fma_f32 v[46:47], s[4:5], v[166:167], v[46:47] op_sel_hi:[0,1,1]
	v_cvt_scalef32_pk_f32_fp4 v[170:171], v37, 1.0 op_sel:[1,0,0]
	v_pk_fma_f32 v[44:45], s[4:5], v[168:169], v[44:45] op_sel_hi:[0,1,1]
	v_cvt_scalef32_pk_f32_fp4 v[172:173], v37, 1.0 op_sel:[0,1,0]
	v_pk_fma_f32 v[42:43], s[4:5], v[170:171], v[42:43] op_sel_hi:[0,1,1]
	v_cvt_scalef32_pk_f32_fp4 v[174:175], v37, 1.0 op_sel:[1,1,0]
	v_pk_fma_f32 v[54:55], s[4:5], v[172:173], v[54:55] op_sel_hi:[0,1,1]
	v_pk_fma_f32 v[56:57], s[4:5], v[174:175], v[56:57] op_sel_hi:[0,1,1]
	global_load_dwordx2 v[36:37], v146, s[52:53]
	s_waitcnt vmcnt(15)
	v_readlane_b32 s4, v12, 19
	v_cvt_scalef32_pk_f32_fp4 v[160:161], v34, 1.0
	v_cvt_scalef32_pk_f32_fp4 v[162:163], v34, 1.0 op_sel:[1,0,0]
	v_pk_fma_f32 v[52:53], s[4:5], v[160:161], v[52:53] op_sel_hi:[0,1,1]
	v_cvt_scalef32_pk_f32_fp4 v[164:165], v34, 1.0 op_sel:[0,1,0]
	v_pk_fma_f32 v[50:51], s[4:5], v[162:163], v[50:51] op_sel_hi:[0,1,1]
	v_cvt_scalef32_pk_f32_fp4 v[166:167], v34, 1.0 op_sel:[1,1,0]
	v_pk_fma_f32 v[48:49], s[4:5], v[164:165], v[48:49] op_sel_hi:[0,1,1]
	v_cvt_scalef32_pk_f32_fp4 v[168:169], v35, 1.0
	v_pk_fma_f32 v[46:47], s[4:5], v[166:167], v[46:47] op_sel_hi:[0,1,1]
	v_cvt_scalef32_pk_f32_fp4 v[170:171], v35, 1.0 op_sel:[1,0,0]
	v_pk_fma_f32 v[44:45], s[4:5], v[168:169], v[44:45] op_sel_hi:[0,1,1]
	v_cvt_scalef32_pk_f32_fp4 v[172:173], v35, 1.0 op_sel:[0,1,0]
	v_pk_fma_f32 v[42:43], s[4:5], v[170:171], v[42:43] op_sel_hi:[0,1,1]
	v_cvt_scalef32_pk_f32_fp4 v[174:175], v35, 1.0 op_sel:[1,1,0]
	v_pk_fma_f32 v[54:55], s[4:5], v[172:173], v[54:55] op_sel_hi:[0,1,1]
	v_pk_fma_f32 v[56:57], s[4:5], v[174:175], v[56:57] op_sel_hi:[0,1,1]
	global_load_dwordx2 v[34:35], v147, s[52:53]
	s_add_i32 s5, s5, 16
	s_cmpk_eq_i32 s5, 0x1f0
	s_cbranch_scc0 .LBB0_1075
	v_add_u32_e32 v135, 0x1e0, v120
	ds_read2st64_b32 v[104:105], v135 offset1:6
	ds_read2st64_b32 v[102:103], v135 offset0:10 offset1:16
	s_waitcnt vmcnt(0) lgkmcnt(0)
	v_mov_b32_e32 v12, v13
	v_mov_b32_e32 v27, v13
	s_waitcnt vmcnt(8)
	v_dot8c_i32_i4_e32 v12, v82, v4
	v_dot8c_i32_i4_e32 v27, v82, v5
	v_dot8c_i32_i4_e32 v12, v83, v6
	v_dot8c_i32_i4_e32 v27, v83, v7
	v_mov_b32_e32 v76, v13
	v_dot8c_i32_i4_e32 v76, v84, v5
	v_dot8c_i32_i4_e32 v76, v85, v7
	v_lshl_add_u32 v12, v12, 4, v27
	v_mov_b32_e32 v27, v13
	v_dot8c_i32_i4_e32 v27, v84, v4
	v_dot8c_i32_i4_e32 v27, v85, v6
	v_mov_b32_e32 v77, v13
	v_dot8c_i32_i4_e32 v77, v74, v5
	v_dot8c_i32_i4_e32 v77, v75, v7
	v_lshl_add_u32 v27, v27, 4, v76
	v_mov_b32_e32 v76, v13
	v_dot8c_i32_i4_e32 v76, v74, v4
	v_dot8c_i32_i4_e32 v76, v75, v6
	v_mov_b32_e32 v75, v13
	v_dot8c_i32_i4_e32 v75, v80, v4
	v_mov_b32_e32 v4, v13
	v_dot8c_i32_i4_e32 v4, v80, v5
	v_dot8c_i32_i4_e32 v75, v81, v6
	v_dot8c_i32_i4_e32 v4, v81, v7
	v_lshl_add_u32 v74, v76, 4, v77
	v_cndmask_b32_e64 v6, v74, v12, s[0:1]
	v_cvt_scalef32_pk_f32_fp4 v[76:77], v72, 1.0 op_sel:[1,1,0]
	v_lshl_add_u32 v4, v75, 4, v4
	v_cndmask_b32_e64 v5, v27, v4, s[0:1]
	v_cndmask_b32_e64 v4, v4, v27, s[0:1]
	v_cvt_scalef32_pk_f32_fp4 v[78:79], v73, 1.0
	v_cvt_scalef32_pk_f32_fp4 v[80:81], v73, 1.0 op_sel:[1,0,0]
	v_add_u32_dpp v4, v4, v5 quad_perm:[1,0,3,2] row_mask:0xf bank_mask:0xf bound_ctrl:1
	v_cndmask_b32_e64 v5, v12, v74, s[0:1]
	v_cvt_scalef32_pk_f32_fp4 v[74:75], v72, 1.0 op_sel:[0,1,0]
	v_cvt_scalef32_pk_f32_fp4 v[82:83], v73, 1.0 op_sel:[0,1,0]
	v_add_u32_dpp v5, v6, v5 quad_perm:[1,0,3,2] row_mask:0xf bank_mask:0xf bound_ctrl:1
	v_cndmask_b32_e64 v6, v5, v4, s[2:3]
	v_cndmask_b32_e64 v4, v4, v5, s[2:3]
	v_cvt_scalef32_pk_f32_fp4 v[84:85], v70, 1.0
	v_lshl_add_u64 v[28:29], v[22:23], 0, v[28:29]
	v_add_u32_dpp v4, v4, v6 quad_perm:[2,3,0,1] row_mask:0xf bank_mask:0xf bound_ctrl:1
	v_mov_b32_e32 v27, v13
	v_cvt_scalef32_pk_f32_fp4 v[108:109], v62, 1.0 op_sel:[0,1,0]
	v_add_u32_dpp v4, v4, v4 row_ror:4 row_mask:0xf bank_mask:0xf bound_ctrl:1
	s_nop 1
	v_add_u32_dpp v4, v4, v4 row_ror:8 row_mask:0xf bank_mask:0xf bound_ctrl:1
	v_mov_b32_e32 v5, v4
	s_nop 1
	v_permlane16_swap_b32_e32 v4, v5
	v_add_u32_e32 v4, v4, v5
	v_mov_b32_e32 v5, v4
	s_nop 1
	v_permlane32_swap_b32_e32 v4, v5
	v_add_u32_e32 v4, v5, v4
	v_cvt_f32_i32_e32 v4, v4
	v_mul_f32_e32 v4, v105, v4
	v_fma_f32 v5, |v4|, s39, 1.0
	v_rcp_f32_e32 v5, v5
	v_mul_f32_e32 v7, v4, v4
	v_mul_f32_e32 v7, 0xbf38aa3b, v7
	v_exp_f32_e32 v7, v7
	v_fmamk_f32 v6, v5, 0x3f07dc22, v129
	v_fmaak_f32 v6, v5, v6, 0x3f35f0e3
	v_fmaak_f32 v6, v5, v6, 0xbe11a98e
	v_fmaak_f32 v6, v5, v6, 0x3e027906
	v_mul_f32_e32 v5, v5, v6
	v_mul_f32_e32 v5, v7, v5
	v_mul_f32_e32 v6, v4, v5
	v_fma_f32 v5, -v4, v5, v4
	v_cmp_gt_f32_e32 vcc, 0, v4
	s_nop 1
	v_cndmask_b32_e32 v4, v5, v6, vcc
	v_mul_f32_e32 v12, v104, v4
	v_cvt_scalef32_pk_f32_fp4 v[4:5], v72, 1.0
	v_readlane_b32 s4, v12, 0
	v_cvt_scalef32_pk_f32_fp4 v[6:7], v72, 1.0 op_sel:[1,0,0]
	v_cvt_scalef32_pk_f32_fp4 v[72:73], v73, 1.0 op_sel:[1,1,0]
	v_pk_fma_f32 v[4:5], s[4:5], v[4:5], v[100:101] op_sel_hi:[0,1,1]
	v_pk_fma_f32 v[6:7], s[4:5], v[6:7], v[98:99] op_sel_hi:[0,1,1]
	v_pk_fma_f32 v[74:75], s[4:5], v[74:75], v[96:97] op_sel_hi:[0,1,1]
	v_pk_fma_f32 v[76:77], s[4:5], v[76:77], v[94:95] op_sel_hi:[0,1,1]
; __device__ __forceinline__ float bf_lo(unsigned u) { return __uint_as_float(u << 16); }
; __device__ __forceinline__ float bf_hi(unsigned u) { return __uint_as_float(u & 0xffff0000u); }
; __device__ __forceinline__ void p3_axpy(const u32x2 (&vr)[4], float ws, f32x2 (&acc)[8]) {
; #pragma unroll
;     for (int u = 0; u < 4; u++) {
;         const int la = ((u >> 1) & 1) | ((u & 1) << 1);
;         const float wu = __builtin_bit_cast(float, __builtin_amdgcn_readlane(__builtin_bit_cast(int, ws), la));
;         const f32x2 w2 = {wu, wu};
;         const unsigned vw[2] = {vr[u].x, vr[u].y};
; #pragma unroll
;         for (int i = 0; i < 2; i++) {
;             acc[i * 4 + 0] = __builtin_elementwise_fma(w2, __builtin_amdgcn_cvt_scalef32_pk_f32_fp4(vw[i], 1.0f, 0), acc[i * 4 + 0]);
;             acc[i * 4 + 1] = __builtin_elementwise_fma(w2, __builtin_amdgcn_cvt_scalef32_pk_f32_fp4(vw[i], 1.0f, 1), acc[i * 4 + 1]);
;             acc[i * 4 + 2] = __builtin_elementwise_fma(w2, __builtin_amdgcn_cvt_scalef32_pk_f32_fp4(vw[i], 1.0f, 2), acc[i * 4 + 2]);
;             acc[i * 4 + 3] = __builtin_elementwise_fma(w2, __builtin_amdgcn_cvt_scalef32_pk_f32_fp4(vw[i], 1.0f, 3), acc[i * 4 + 3]);
;         }
;     }
; }
; __device__ __forceinline__ void p3_finish(const Params& p, float* dstp, int tok, int lane, const f32x2 (&acc)[8], float* tr) {
;     const float* mod = (const float*)(p.ws + OFF_MOD);
;     const int b = tok >> 11;
;     float own[16];
; #pragma unroll
;     for (int i = 0; i < 16; i++) own[i] = acc[i >> 1][i & 1];
;     const int d0 = lane * 16;
;     float x2[16];
;     float ss = 0.f;
;     const bf16_t* x1b = (const bf16_t*)(p.ws + OFF_X1B) + (size_t)tok * DM + d0;
;     const u32x4 xa = *(const u32x4*)x1b, xb = *(const u32x4*)(x1b + 8);
;     const unsigned xw[8] = {xa.x, xa.y, xa.z, xa.w, xb.x, xb.y, xb.z, xb.w};
; #pragma unroll
;     for (int i = 0; i < 4; i++) {
;         const int d = d0 + i * 4;
;         const f32x4 xv = {bf_lo(xw[2 * i]), bf_hi(xw[2 * i]), bf_lo(xw[2 * i + 1]), bf_hi(xw[2 * i + 1])};
;         const f32x4 gt = *(const f32x4*)(mod + b * 6144 + 5 * 1024 + d);
; #pragma unroll
;         for (int j = 0; j < 4; j++) { const float v = xv[j] + gt[j] * own[i * 4 + j]; x2[i * 4 + j] = v; ss += v * v; }
;     }
;     ss = wave_sum(ss);
	v_pk_fma_f32 v[78:79], s[4:5], v[78:79], v[92:93] op_sel_hi:[0,1,1]
	v_pk_fma_f32 v[80:81], s[4:5], v[80:81], v[90:91] op_sel_hi:[0,1,1]
	v_pk_fma_f32 v[82:83], s[4:5], v[82:83], v[88:89] op_sel_hi:[0,1,1]
	v_pk_fma_f32 v[72:73], s[4:5], v[72:73], v[86:87] op_sel_hi:[0,1,1]
	v_readlane_b32 s4, v12, 2
	s_nop 1
	v_pk_fma_f32 v[4:5], s[4:5], v[84:85], v[4:5] op_sel_hi:[0,1,1]
	v_cvt_scalef32_pk_f32_fp4 v[84:85], v70, 1.0 op_sel:[1,0,0]
	v_pk_fma_f32 v[84:85], s[4:5], v[84:85], v[6:7] op_sel_hi:[0,1,1]
	v_cvt_scalef32_pk_f32_fp4 v[6:7], v70, 1.0 op_sel:[0,1,0]
	v_pk_fma_f32 v[90:91], s[4:5], v[6:7], v[74:75] op_sel_hi:[0,1,1]
	v_cvt_scalef32_pk_f32_fp4 v[6:7], v70, 1.0 op_sel:[1,1,0]
	v_pk_fma_f32 v[92:93], s[4:5], v[6:7], v[76:77] op_sel_hi:[0,1,1]
	v_cvt_scalef32_pk_f32_fp4 v[6:7], v71, 1.0
	v_pk_fma_f32 v[94:95], s[4:5], v[6:7], v[78:79] op_sel_hi:[0,1,1]
	v_cvt_scalef32_pk_f32_fp4 v[6:7], v71, 1.0 op_sel:[1,0,0]
	v_pk_fma_f32 v[96:97], s[4:5], v[6:7], v[80:81] op_sel_hi:[0,1,1]
	v_cvt_scalef32_pk_f32_fp4 v[6:7], v71, 1.0 op_sel:[0,1,0]
	v_pk_fma_f32 v[98:99], s[4:5], v[6:7], v[82:83] op_sel_hi:[0,1,1]
	v_cvt_scalef32_pk_f32_fp4 v[6:7], v71, 1.0 op_sel:[1,1,0]
	v_pk_fma_f32 v[100:101], s[4:5], v[6:7], v[72:73] op_sel_hi:[0,1,1]
	v_ashrrev_i32_e32 v6, 11, v8
	v_mul_i32_i24_e32 v6, 0x1800, v6
	v_ashrrev_i32_e32 v7, 31, v6
	v_lshl_add_u64 v[6:7], v[6:7], 2, s[22:23]
	v_readlane_b32 s4, v12, 1
	global_load_dwordx4 v[70:73], v[28:29], off offset:16
	global_load_dwordx4 v[74:77], v[28:29], off
	v_lshl_add_u64 v[28:29], v[6:7], 0, v[26:27]
	v_cvt_scalef32_pk_f32_fp4 v[82:83], v62, 1.0
	v_add_co_u32_e32 v6, vcc, s40, v28
	v_pk_fma_f32 v[104:105], s[4:5], v[82:83], v[4:5] op_sel_hi:[0,1,1]
	v_cvt_scalef32_pk_f32_fp4 v[4:5], v62, 1.0 op_sel:[1,0,0]
	v_addc_co_u32_e32 v7, vcc, 0, v29, vcc
	v_pk_fma_f32 v[106:107], s[4:5], v[4:5], v[84:85] op_sel_hi:[0,1,1]
	v_lshl_add_u64 v[4:5], v[28:29], 0, s[30:31]
	v_pk_fma_f32 v[28:29], s[4:5], v[108:109], v[90:91] op_sel_hi:[0,1,1]
	v_cvt_scalef32_pk_f32_fp4 v[90:91], v62, 1.0 op_sel:[1,1,0]
	v_pk_fma_f32 v[108:109], s[4:5], v[90:91], v[92:93] op_sel_hi:[0,1,1]
	v_cvt_scalef32_pk_f32_fp4 v[90:91], v63, 1.0
	global_load_dwordx4 v[78:81], v[6:7], off
	v_pk_fma_f32 v[94:95], s[4:5], v[90:91], v[94:95] op_sel_hi:[0,1,1]
	v_cvt_scalef32_pk_f32_fp4 v[90:91], v63, 1.0 op_sel:[1,0,0]
	global_load_dwordx4 v[82:85], v[4:5], off offset:32
	global_load_dwordx4 v[86:89], v[4:5], off offset:16
	v_pk_fma_f32 v[96:97], s[4:5], v[90:91], v[96:97] op_sel_hi:[0,1,1]
	v_cvt_scalef32_pk_f32_fp4 v[90:91], v63, 1.0 op_sel:[0,1,0]
	v_cvt_scalef32_pk_f32_fp4 v[62:63], v63, 1.0 op_sel:[1,1,0]
	v_pk_fma_f32 v[98:99], s[4:5], v[90:91], v[98:99] op_sel_hi:[0,1,1]
	v_pk_fma_f32 v[62:63], s[4:5], v[62:63], v[100:101] op_sel_hi:[0,1,1]
	v_readlane_b32 s4, v12, 3
	s_waitcnt vmcnt(11)
	v_cvt_scalef32_pk_f32_fp4 v[90:91], v58, 1.0
	v_mov_b32_e32 v12, v13
	v_pk_fma_f32 v[100:101], s[4:5], v[90:91], v[104:105] op_sel_hi:[0,1,1]
	global_load_dwordx4 v[90:93], v[4:5], off offset:48
	v_cvt_scalef32_pk_f32_fp4 v[104:105], v58, 1.0 op_sel:[1,0,0]
	v_pk_fma_f32 v[104:105], s[4:5], v[104:105], v[106:107] op_sel_hi:[0,1,1]
	v_cvt_scalef32_pk_f32_fp4 v[106:107], v58, 1.0 op_sel:[0,1,0]
	v_pk_fma_f32 v[28:29], s[4:5], v[106:107], v[28:29] op_sel_hi:[0,1,1]
	v_cvt_scalef32_pk_f32_fp4 v[106:107], v58, 1.0 op_sel:[1,1,0]
	v_pk_fma_f32 v[106:107], s[4:5], v[106:107], v[108:109] op_sel_hi:[0,1,1]
	v_cvt_scalef32_pk_f32_fp4 v[108:109], v59, 1.0
	v_pk_fma_f32 v[94:95], s[4:5], v[108:109], v[94:95] op_sel_hi:[0,1,1]
	v_cvt_scalef32_pk_f32_fp4 v[108:109], v59, 1.0 op_sel:[1,0,0]
	s_waitcnt vmcnt(9)
	v_dot8c_i32_i4_e32 v12, v64, v0
	v_dot8c_i32_i4_e32 v27, v64, v1
	v_pk_fma_f32 v[96:97], s[4:5], v[108:109], v[96:97] op_sel_hi:[0,1,1]
	v_cvt_scalef32_pk_f32_fp4 v[108:109], v59, 1.0 op_sel:[0,1,0]
	v_cvt_scalef32_pk_f32_fp4 v[58:59], v59, 1.0 op_sel:[1,1,0]
	v_dot8c_i32_i4_e32 v12, v65, v2
	v_dot8c_i32_i4_e32 v27, v65, v3
	v_pk_fma_f32 v[98:99], s[4:5], v[108:109], v[98:99] op_sel_hi:[0,1,1]
	v_pk_fma_f32 v[108:109], s[4:5], v[58:59], v[62:63] op_sel_hi:[0,1,1]
	v_mov_b32_e32 v58, v13
	v_lshl_add_u32 v12, v12, 4, v27
	v_mov_b32_e32 v27, v13
	v_dot8c_i32_i4_e32 v27, v68, v0
	v_dot8c_i32_i4_e32 v58, v68, v1
	v_dot8c_i32_i4_e32 v27, v69, v2
	v_dot8c_i32_i4_e32 v58, v69, v3
	v_mov_b32_e32 v59, v13
	s_waitcnt vmcnt(7)
	v_dot8c_i32_i4_e32 v59, v60, v1
	v_dot8c_i32_i4_e32 v59, v61, v3
	v_lshl_add_u32 v27, v27, 4, v58
	v_mov_b32_e32 v58, v13
	v_dot8c_i32_i4_e32 v58, v60, v0
	v_dot8c_i32_i4_e32 v58, v61, v2
	s_waitcnt vmcnt(4)
	v_lshlrev_b32_e32 v110, 16, v74
	s_nop 0
	v_lshl_add_u32 v58, v58, 4, v59
	v_mov_b32_e32 v59, v13
	v_dot8c_i32_i4_e32 v59, v66, v0
	v_mov_b32_e32 v0, v13
	v_dot8c_i32_i4_e32 v0, v66, v1
	v_dot8c_i32_i4_e32 v59, v67, v2
	v_dot8c_i32_i4_e32 v0, v67, v3
	v_cndmask_b32_e64 v2, v58, v12, s[0:1]
	v_and_b32_e32 v111, 0xffff0000, v74
	v_lshlrev_b32_e32 v74, 16, v75
	v_lshl_add_u32 v0, v59, 4, v0
	v_cndmask_b32_e64 v1, v27, v0, s[0:1]
	v_cndmask_b32_e64 v0, v0, v27, s[0:1]
	v_and_b32_e32 v75, 0xffff0000, v75
	s_waitcnt vmcnt(3)
	v_pk_fma_f32 v[74:75], v[104:105], v[80:81], v[74:75]
	v_add_u32_dpp v0, v0, v1 quad_perm:[1,0,3,2] row_mask:0xf bank_mask:0xf bound_ctrl:1
	v_cndmask_b32_e64 v1, v12, v58, s[0:1]
	v_lshlrev_b32_e32 v104, 16, v76
	v_and_b32_e32 v105, 0xffff0000, v76
	v_add_u32_dpp v1, v2, v1 quad_perm:[1,0,3,2] row_mask:0xf bank_mask:0xf bound_ctrl:1
	v_cndmask_b32_e64 v12, v1, v0, s[2:3]
	v_cndmask_b32_e64 v27, v0, v1, s[2:3]
	global_load_dwordx4 v[0:3], v[24:25], off offset:48
	global_load_dwordx4 v[58:61], v[24:25], off offset:32
	global_load_dwordx4 v[62:65], v[24:25], off offset:16
	global_load_dwordx4 v[66:69], v[24:25], off
	v_pk_fma_f32 v[78:79], v[100:101], v[78:79], v[110:111]
	s_waitcnt vmcnt(5)
; __device__ __forceinline__ float bf_lo(unsigned u) { return __uint_as_float(u << 16); }
; __device__ __forceinline__ float bf_hi(unsigned u) { return __uint_as_float(u & 0xffff0000u); }
; __device__ __forceinline__ float wave_sum(float v) {
; #pragma unroll
;     for (int o = 32; o > 0; o >>= 1) v += __shfl_xor(v, o, 64);
;     return v;
; }
; __device__ __forceinline__ void p3_finish(const Params& p, float* dstp, int tok, int lane, const f32x2 (&acc)[8], float* tr) {
;     ...
; #pragma unroll
;     for (int i = 0; i < 4; i++) {
;         const int d = d0 + i * 4;
;         const f32x4 xv = {bf_lo(xw[2 * i]), bf_hi(xw[2 * i]), bf_lo(xw[2 * i + 1]), bf_hi(xw[2 * i + 1])};
;         const f32x4 gt = *(const f32x4*)(mod + b * 6144 + 5 * 1024 + d);
; #pragma unroll
;         for (int j = 0; j < 4; j++) { const float v = xv[j] + gt[j] * own[i * 4 + j]; x2[i * 4 + j] = v; ss += v * v; }
;     }
;     ss = wave_sum(ss);
;     const float rstd = rsqrtf(ss * (1.f / 1024.f) + 1e-6f);
; #pragma unroll
;     for (int i = 0; i < 4; i++) {
;         const int d = d0 + i * 4;
;         const f32x4 fg = *(const f32x4*)(p.final_g + d);
;         f32x4 o;
; #pragma unroll
;         for (int j = 0; j < 4; j++) o[j] = x2[i * 4 + j] * rstd * fg[j];
;         *(f32x4*)(tr + d) = o;
;     }
;     __builtin_amdgcn_fence(__ATOMIC_RELEASE, "wavefront");
;     __builtin_amdgcn_wave_barrier();
;     __builtin_amdgcn_fence(__ATOMIC_ACQUIRE, "wavefront");
; #pragma unroll
;     for (int j = 0; j < 4; j++) {
;         const f32x4 v = *(const f32x4*)(tr + j * 256 + lane * 4);
;         *(f32x4*)(dstp + (size_t)tok * DM + j * 256 + lane * 4) = v;
;     }
;     __builtin_amdgcn_wave_barrier();
; }
	v_pk_fma_f32 v[28:29], v[28:29], v[86:87], v[104:105]
	v_lshlrev_b32_e32 v104, 16, v70
	v_and_b32_e32 v105, 0xffff0000, v70
	v_lshlrev_b32_e32 v70, 16, v71
	v_and_b32_e32 v71, 0xffff0000, v71
	v_pk_mul_f32 v[100:101], v[78:79], v[78:79]
	v_pk_fma_f32 v[70:71], v[96:97], v[84:85], v[70:71]
	v_lshlrev_b32_e32 v96, 16, v72
	v_and_b32_e32 v97, 0xffff0000, v72
	v_pk_mul_f32 v[80:81], v[74:75], v[74:75]
	s_waitcnt vmcnt(4)
	v_pk_fma_f32 v[90:91], v[98:99], v[90:91], v[96:97]
	v_add_f32_e32 v98, v100, v101
	v_add_f32_e32 v80, v80, v98
	v_pk_mul_f32 v[86:87], v[28:29], v[28:29]
	v_lshlrev_b32_e32 v76, 16, v77
	v_and_b32_e32 v77, 0xffff0000, v77
	v_add_f32_e32 v80, v81, v80
	v_pk_fma_f32 v[76:77], v[106:107], v[88:89], v[76:77]
	v_add_f32_e32 v80, v86, v80
	v_pk_mul_f32 v[88:89], v[76:77], v[76:77]
	v_add_f32_e32 v80, v87, v80
	v_pk_fma_f32 v[82:83], v[94:95], v[82:83], v[104:105]
	v_add_f32_e32 v80, v88, v80
	v_pk_mul_f32 v[94:95], v[82:83], v[82:83]
	v_add_f32_e32 v80, v89, v80
	v_add_f32_e32 v80, v94, v80
	v_pk_mul_f32 v[84:85], v[70:71], v[70:71]
	v_add_f32_e32 v80, v95, v80
	v_add_f32_e32 v80, v84, v80
	v_pk_mul_f32 v[96:97], v[90:91], v[90:91]
	v_lshlrev_b32_e32 v72, 16, v73
	v_and_b32_e32 v73, 0xffff0000, v73
	v_add_f32_e32 v80, v85, v80
	v_pk_fma_f32 v[72:73], v[108:109], v[92:93], v[72:73]
	v_add_f32_e32 v80, v96, v80
	v_pk_mul_f32 v[92:93], v[72:73], v[72:73]
	v_add_f32_e32 v80, v97, v80
	v_add_f32_e32 v80, v92, v80
	v_add_f32_e32 v80, v93, v80
	s_nop 1
	v_add_f32_dpp v80, v80, v80 row_ror:8 row_mask:0xf bank_mask:0xf
	s_nop 1
	v_add_f32_dpp v80, v80, v80 row_ror:4 row_mask:0xf bank_mask:0xf
	s_nop 1
	v_add_f32_dpp v80, v80, v80 row_ror:2 row_mask:0xf bank_mask:0xf
	s_nop 1
	v_add_f32_dpp v80, v80, v80 row_ror:1 row_mask:0xf bank_mask:0xf
	v_mov_b32_e32 v81, v80
	s_nop 1
	v_permlane16_swap_b32_e32 v80, v81
	v_add_f32_e32 v80, v80, v81
	v_mov_b32_e32 v81, v80
	s_nop 1
	v_permlane32_swap_b32_e32 v80, v81
	v_add_f32_e32 v80, v80, v81
	v_add_u32_dpp v12, v27, v12 quad_perm:[2,3,0,1] row_mask:0xf bank_mask:0xf bound_ctrl:1
	s_waitcnt lgkmcnt(0)
	s_nop 1
	v_add_u32_dpp v12, v12, v12 row_ror:4 row_mask:0xf bank_mask:0xf bound_ctrl:1
	s_nop 1
	v_add_u32_dpp v12, v12, v12 row_ror:8 row_mask:0xf bank_mask:0xf bound_ctrl:1
	v_mov_b32_e32 v27, v12
	s_nop 1
	v_permlane16_swap_b32_e32 v12, v27
	v_add_u32_e32 v12, v12, v27
	v_mov_b32_e32 v27, v12
	s_nop 1
	v_permlane32_swap_b32_e32 v12, v27
	v_add_u32_e32 v12, v27, v12
	s_waitcnt lgkmcnt(0)
	v_cvt_f32_i32_e32 v12, v12
	s_waitcnt lgkmcnt(0)
	v_mul_f32_e32 v81, v103, v12
	v_fma_f32 v12, |v81|, s39, 1.0
	v_rcp_f32_e32 v12, v12
	s_waitcnt lgkmcnt(0)
	v_fmamk_f32 v84, v12, 0x3f07dc22, v129
	v_fmaak_f32 v84, v12, v84, 0x3f35f0e3
	v_fmaak_f32 v84, v12, v84, 0xbe11a98e
	v_fmaak_f32 v84, v12, v84, 0x3e027906
	s_waitcnt lgkmcnt(0)
	v_mov_b32_e32 v27, v80
	v_mul_f32_e32 v12, v12, v84
	v_mul_f32_e32 v84, v81, v81
	v_fmamk_f32 v27, v27, 0x3a800000, v130
	v_mul_f32_e32 v84, 0xbf38aa3b, v84
	v_mul_f32_e32 v80, 0x4b800000, v27
	v_cmp_gt_f32_e32 vcc, s38, v27
	v_exp_f32_e32 v84, v84
	s_nop 0
	v_cndmask_b32_e32 v27, v27, v80, vcc
	v_rsq_f32_e32 v27, v27
	v_mul_f32_e32 v12, v84, v12
	v_mul_f32_e32 v80, v81, v12
	v_fma_f32 v84, -v81, v12, v81
	v_mul_f32_e32 v12, 0x45800000, v27
	v_cndmask_b32_e32 v12, v27, v12, vcc
	v_pk_mul_f32 v[78:79], v[78:79], v[12:13] op_sel_hi:[1,0]
	v_pk_mul_f32 v[74:75], v[74:75], v[12:13] op_sel_hi:[1,0]
	s_waitcnt vmcnt(0)
	v_pk_mul_f32 v[66:67], v[66:67], v[78:79]
	v_pk_mul_f32 v[68:69], v[68:69], v[74:75]
	ds_write_b128 v118, v[66:69]
	v_pk_mul_f32 v[28:29], v[28:29], v[12:13] op_sel_hi:[1,0]
	v_pk_mul_f32 v[66:67], v[76:77], v[12:13] op_sel_hi:[1,0]
	v_pk_mul_f32 v[62:63], v[62:63], v[28:29]
	v_pk_mul_f32 v[64:65], v[64:65], v[66:67]
	ds_write_b128 v118, v[62:65] offset:16
	v_pk_mul_f32 v[28:29], v[82:83], v[12:13] op_sel_hi:[1,0]
	v_pk_mul_f32 v[62:63], v[70:71], v[12:13] op_sel_hi:[1,0]
	v_pk_mul_f32 v[58:59], v[58:59], v[28:29]
	v_pk_mul_f32 v[60:61], v[60:61], v[62:63]
	ds_write_b128 v118, v[58:61] offset:32
	v_pk_mul_f32 v[28:29], v[90:91], v[12:13] op_sel_hi:[1,0]
	v_pk_mul_f32 v[58:59], v[72:73], v[12:13] op_sel_hi:[1,0]
	v_pk_mul_f32 v[0:1], v[0:1], v[28:29]
	v_pk_mul_f32 v[2:3], v[2:3], v[58:59]
	ds_write_b128 v118, v[0:3] offset:48
	ds_read_b128 v[0:3], v128
	ds_read_b128 v[58:61], v128 offset:1024
	ds_read_b128 v[62:65], v128 offset:2048
	ds_read_b128 v[66:69], v128 offset:3072
	v_lshlrev_b64 v[28:29], 12, v[8:9]
	v_lshl_add_u64 v[28:29], v[18:19], 0, v[28:29]
	s_waitcnt lgkmcnt(3)
	global_store_dwordx4 v[28:29], v[0:3], off
	s_waitcnt lgkmcnt(2)
	global_store_dwordx4 v[28:29], v[58:61], off offset:1024
	s_waitcnt lgkmcnt(1)
	global_store_dwordx4 v[28:29], v[62:65], off offset:2048
	s_waitcnt lgkmcnt(0)
	global_store_dwordx4 v[28:29], v[66:69], off offset:3072
	v_lshl_add_u64 v[28:29], v[22:23], 0, v[32:33]
	global_load_dwordx4 v[0:3], v[28:29], off offset:16
	global_load_dwordx4 v[58:61], v[28:29], off
	global_load_dwordx4 v[62:65], v[6:7], off
	v_cmp_gt_f32_e32 vcc, 0, v81
	global_load_dwordx4 v[66:69], v[4:5], off offset:32
	global_load_dwordx4 v[70:73], v[4:5], off offset:16
	v_cndmask_b32_e32 v6, v84, v80, vcc
	v_mul_f32_e32 v9, v102, v6
	v_cvt_scalef32_pk_f32_fp4 v[6:7], v40, 1.0
	v_readlane_b32 s4, v9, 0
	v_add_u32_e32 v8, s36, v8
	s_waitcnt vmcnt(3)
; __device__ __forceinline__ float bf_lo(unsigned u) { return __uint_as_float(u << 16); }
; __device__ __forceinline__ float bf_hi(unsigned u) { return __uint_as_float(u & 0xffff0000u); }
; __device__ __forceinline__ void p3_axpy(const u32x2 (&vr)[4], float ws, f32x2 (&acc)[8]) {
; #pragma unroll
;     for (int u = 0; u < 4; u++) {
;         const int la = ((u >> 1) & 1) | ((u & 1) << 1);
;         const float wu = __builtin_bit_cast(float, __builtin_amdgcn_readlane(__builtin_bit_cast(int, ws), la));
;         const f32x2 w2 = {wu, wu};
;         const unsigned vw[2] = {vr[u].x, vr[u].y};
; #pragma unroll
;         for (int i = 0; i < 2; i++) {
;             acc[i * 4 + 0] = __builtin_elementwise_fma(w2, __builtin_amdgcn_cvt_scalef32_pk_f32_fp4(vw[i], 1.0f, 0), acc[i * 4 + 0]);
;             acc[i * 4 + 1] = __builtin_elementwise_fma(w2, __builtin_amdgcn_cvt_scalef32_pk_f32_fp4(vw[i], 1.0f, 1), acc[i * 4 + 1]);
;             acc[i * 4 + 2] = __builtin_elementwise_fma(w2, __builtin_amdgcn_cvt_scalef32_pk_f32_fp4(vw[i], 1.0f, 2), acc[i * 4 + 2]);
;             acc[i * 4 + 3] = __builtin_elementwise_fma(w2, __builtin_amdgcn_cvt_scalef32_pk_f32_fp4(vw[i], 1.0f, 3), acc[i * 4 + 3]);
;         }
;     }
; }
; __device__ __forceinline__ void p3_finish(const Params& p, float* dstp, int tok, int lane, const f32x2 (&acc)[8], float* tr) {
;     ...
;     const bf16_t* x1b = (const bf16_t*)(p.ws + OFF_X1B) + (size_t)tok * DM + d0;
;     const u32x4 xa = *(const u32x4*)x1b, xb = *(const u32x4*)(x1b + 8);
;     const unsigned xw[8] = {xa.x, xa.y, xa.z, xa.w, xb.x, xb.y, xb.z, xb.w};
; #pragma unroll
;     for (int i = 0; i < 4; i++) {
;         const int d = d0 + i * 4;
;         const f32x4 xv = {bf_lo(xw[2 * i]), bf_hi(xw[2 * i]), bf_lo(xw[2 * i + 1]), bf_hi(xw[2 * i + 1])};
;         const f32x4 gt = *(const f32x4*)(mod + b * 6144 + 5 * 1024 + d);
	v_lshlrev_b32_e32 v78, 16, v58
	v_pk_fma_f32 v[28:29], s[4:5], v[6:7], v[52:53] op_sel_hi:[0,1,1]
	v_cvt_scalef32_pk_f32_fp4 v[6:7], v40, 1.0 op_sel:[1,0,0]
	v_pk_fma_f32 v[32:33], s[4:5], v[6:7], v[50:51] op_sel_hi:[0,1,1]
	v_cvt_scalef32_pk_f32_fp4 v[6:7], v40, 1.0 op_sel:[0,1,0]
	v_pk_fma_f32 v[48:49], s[4:5], v[6:7], v[48:49] op_sel_hi:[0,1,1]
	v_cvt_scalef32_pk_f32_fp4 v[6:7], v40, 1.0 op_sel:[1,1,0]
	v_pk_fma_f32 v[46:47], s[4:5], v[6:7], v[46:47] op_sel_hi:[0,1,1]
	v_cvt_scalef32_pk_f32_fp4 v[6:7], v41, 1.0
	v_pk_fma_f32 v[44:45], s[4:5], v[6:7], v[44:45] op_sel_hi:[0,1,1]
	v_cvt_scalef32_pk_f32_fp4 v[6:7], v41, 1.0 op_sel:[1,0,0]
	v_pk_fma_f32 v[42:43], s[4:5], v[6:7], v[42:43] op_sel_hi:[0,1,1]
	v_cvt_scalef32_pk_f32_fp4 v[6:7], v41, 1.0 op_sel:[0,1,0]
	v_pk_fma_f32 v[50:51], s[4:5], v[6:7], v[54:55] op_sel_hi:[0,1,1]
	v_cvt_scalef32_pk_f32_fp4 v[6:7], v41, 1.0 op_sel:[1,1,0]
	v_pk_fma_f32 v[40:41], s[4:5], v[6:7], v[56:57] op_sel_hi:[0,1,1]
	global_load_dwordx4 v[4:7], v[4:5], off offset:48
	v_readlane_b32 s4, v9, 2
	v_cvt_scalef32_pk_f32_fp4 v[52:53], v38, 1.0
	v_and_b32_e32 v79, 0xffff0000, v58
	v_pk_fma_f32 v[28:29], s[4:5], v[52:53], v[28:29] op_sel_hi:[0,1,1]
	v_cvt_scalef32_pk_f32_fp4 v[52:53], v38, 1.0 op_sel:[1,0,0]
	v_pk_fma_f32 v[32:33], s[4:5], v[52:53], v[32:33] op_sel_hi:[0,1,1]
	v_cvt_scalef32_pk_f32_fp4 v[52:53], v38, 1.0 op_sel:[0,1,0]
	v_pk_fma_f32 v[48:49], s[4:5], v[52:53], v[48:49] op_sel_hi:[0,1,1]
	v_cvt_scalef32_pk_f32_fp4 v[52:53], v38, 1.0 op_sel:[1,1,0]
	v_pk_fma_f32 v[46:47], s[4:5], v[52:53], v[46:47] op_sel_hi:[0,1,1]
	v_cvt_scalef32_pk_f32_fp4 v[52:53], v39, 1.0
	v_pk_fma_f32 v[44:45], s[4:5], v[52:53], v[44:45] op_sel_hi:[0,1,1]
	v_cvt_scalef32_pk_f32_fp4 v[52:53], v39, 1.0 op_sel:[1,0,0]
	v_pk_fma_f32 v[42:43], s[4:5], v[52:53], v[42:43] op_sel_hi:[0,1,1]
	v_cvt_scalef32_pk_f32_fp4 v[52:53], v39, 1.0 op_sel:[0,1,0]
	v_cvt_scalef32_pk_f32_fp4 v[38:39], v39, 1.0 op_sel:[1,1,0]
	v_pk_fma_f32 v[50:51], s[4:5], v[52:53], v[50:51] op_sel_hi:[0,1,1]
	v_pk_fma_f32 v[38:39], s[4:5], v[38:39], v[40:41] op_sel_hi:[0,1,1]
	v_readlane_b32 s4, v9, 1
	v_cvt_scalef32_pk_f32_fp4 v[40:41], v36, 1.0
	v_lshlrev_b32_e32 v58, 16, v59
	v_pk_fma_f32 v[28:29], s[4:5], v[40:41], v[28:29] op_sel_hi:[0,1,1]
	v_cvt_scalef32_pk_f32_fp4 v[40:41], v36, 1.0 op_sel:[1,0,0]
	v_pk_fma_f32 v[32:33], s[4:5], v[40:41], v[32:33] op_sel_hi:[0,1,1]
	v_cvt_scalef32_pk_f32_fp4 v[40:41], v36, 1.0 op_sel:[0,1,0]
	v_pk_fma_f32 v[40:41], s[4:5], v[40:41], v[48:49] op_sel_hi:[0,1,1]
	v_cvt_scalef32_pk_f32_fp4 v[48:49], v36, 1.0 op_sel:[1,1,0]
	v_pk_fma_f32 v[46:47], s[4:5], v[48:49], v[46:47] op_sel_hi:[0,1,1]
	v_cvt_scalef32_pk_f32_fp4 v[48:49], v37, 1.0
	v_pk_fma_f32 v[44:45], s[4:5], v[48:49], v[44:45] op_sel_hi:[0,1,1]
	v_cvt_scalef32_pk_f32_fp4 v[48:49], v37, 1.0 op_sel:[1,0,0]
	v_pk_fma_f32 v[42:43], s[4:5], v[48:49], v[42:43] op_sel_hi:[0,1,1]
	v_cvt_scalef32_pk_f32_fp4 v[48:49], v37, 1.0 op_sel:[0,1,0]
	v_cvt_scalef32_pk_f32_fp4 v[36:37], v37, 1.0 op_sel:[1,1,0]
	v_pk_fma_f32 v[48:49], s[4:5], v[48:49], v[50:51] op_sel_hi:[0,1,1]
	v_pk_fma_f32 v[36:37], s[4:5], v[36:37], v[38:39] op_sel_hi:[0,1,1]
	v_readlane_b32 s4, v9, 3
	v_cvt_scalef32_pk_f32_fp4 v[38:39], v34, 1.0
	v_and_b32_e32 v59, 0xffff0000, v59
	v_pk_fma_f32 v[28:29], s[4:5], v[38:39], v[28:29] op_sel_hi:[0,1,1]
	v_cvt_scalef32_pk_f32_fp4 v[38:39], v34, 1.0 op_sel:[1,0,0]
	v_pk_fma_f32 v[50:51], s[4:5], v[38:39], v[32:33] op_sel_hi:[0,1,1]
	v_cvt_scalef32_pk_f32_fp4 v[32:33], v34, 1.0 op_sel:[0,1,0]
	v_pk_fma_f32 v[52:53], s[4:5], v[32:33], v[40:41] op_sel_hi:[0,1,1]
	v_cvt_scalef32_pk_f32_fp4 v[32:33], v34, 1.0 op_sel:[1,1,0]
	v_pk_fma_f32 v[54:55], s[4:5], v[32:33], v[46:47] op_sel_hi:[0,1,1]
	v_cvt_scalef32_pk_f32_fp4 v[32:33], v35, 1.0
	v_pk_fma_f32 v[56:57], s[4:5], v[32:33], v[44:45] op_sel_hi:[0,1,1]
	v_cvt_scalef32_pk_f32_fp4 v[32:33], v35, 1.0 op_sel:[1,0,0]
	v_pk_fma_f32 v[74:75], s[4:5], v[32:33], v[42:43] op_sel_hi:[0,1,1]
	v_cvt_scalef32_pk_f32_fp4 v[32:33], v35, 1.0 op_sel:[0,1,0]
	v_pk_fma_f32 v[48:49], s[4:5], v[32:33], v[48:49] op_sel_hi:[0,1,1]
	v_cvt_scalef32_pk_f32_fp4 v[32:33], v35, 1.0 op_sel:[1,1,0]
	v_pk_fma_f32 v[76:77], s[4:5], v[32:33], v[36:37] op_sel_hi:[0,1,1]
	global_load_dwordx4 v[32:35], v[24:25], off offset:48
	global_load_dwordx4 v[36:39], v[24:25], off offset:32
	global_load_dwordx4 v[40:43], v[24:25], off offset:16
	global_load_dwordx4 v[44:47], v[24:25], off
	s_waitcnt vmcnt(7)
; __device__ __forceinline__ float bf_lo(unsigned u) { return __uint_as_float(u << 16); }
; __device__ __forceinline__ float bf_hi(unsigned u) { return __uint_as_float(u & 0xffff0000u); }
; __device__ __forceinline__ void p3_finish(const Params& p, float* dstp, int tok, int lane, const f32x2 (&acc)[8], float* tr) {
;     ...
; #pragma unroll
;     for (int i = 0; i < 4; i++) {
;         const int d = d0 + i * 4;
;         const f32x4 xv = {bf_lo(xw[2 * i]), bf_hi(xw[2 * i]), bf_lo(xw[2 * i + 1]), bf_hi(xw[2 * i + 1])};
;         const f32x4 gt = *(const f32x4*)(mod + b * 6144 + 5 * 1024 + d);
; #pragma unroll
;         for (int j = 0; j < 4; j++) { const float v = xv[j] + gt[j] * own[i * 4 + j]; x2[i * 4 + j] = v; ss += v * v; }
;     }
;     ss = wave_sum(ss);
;     const float rstd = rsqrtf(ss * (1.f / 1024.f) + 1e-6f);
; #pragma unroll
;     for (int i = 0; i < 4; i++) {
;         const int d = d0 + i * 4;
;         const f32x4 fg = *(const f32x4*)(p.final_g + d);
;         f32x4 o;
; #pragma unroll
;         for (int j = 0; j < 4; j++) o[j] = x2[i * 4 + j] * rstd * fg[j];
;         *(f32x4*)(tr + d) = o;
;     }
;     __builtin_amdgcn_fence(__ATOMIC_RELEASE, "wavefront");
;     __builtin_amdgcn_wave_barrier();
;     __builtin_amdgcn_fence(__ATOMIC_ACQUIRE, "wavefront");
; #pragma unroll
;     for (int j = 0; j < 4; j++) {
;         const f32x4 v = *(const f32x4*)(tr + j * 256 + lane * 4);
;         *(f32x4*)(dstp + (size_t)tok * DM + j * 256 + lane * 4) = v;
;     }
;     __builtin_amdgcn_wave_barrier();
; }
	v_pk_fma_f32 v[28:29], v[28:29], v[62:63], v[78:79]
	v_pk_fma_f32 v[50:51], v[50:51], v[64:65], v[58:59]
	v_pk_mul_f32 v[62:63], v[28:29], v[28:29]
	v_pk_mul_f32 v[58:59], v[50:51], v[50:51]
	v_lshlrev_b32_e32 v64, 16, v60
	v_and_b32_e32 v65, 0xffff0000, v60
	v_add_f32_e32 v9, v62, v63
	s_waitcnt vmcnt(5)
	v_pk_fma_f32 v[52:53], v[52:53], v[70:71], v[64:65]
	v_add_f32_e32 v9, v58, v9
	v_pk_mul_f32 v[64:65], v[52:53], v[52:53]
	v_lshlrev_b32_e32 v60, 16, v61
	v_and_b32_e32 v61, 0xffff0000, v61
	v_add_f32_e32 v9, v59, v9
	v_pk_fma_f32 v[54:55], v[54:55], v[72:73], v[60:61]
	v_add_f32_e32 v9, v64, v9
	v_pk_mul_f32 v[60:61], v[54:55], v[54:55]
	v_lshlrev_b32_e32 v70, 16, v0
	v_and_b32_e32 v71, 0xffff0000, v0
	v_add_f32_e32 v9, v65, v9
	v_pk_fma_f32 v[56:57], v[56:57], v[66:67], v[70:71]
	v_add_f32_e32 v9, v60, v9
	v_pk_mul_f32 v[66:67], v[56:57], v[56:57]
	v_lshlrev_b32_e32 v0, 16, v1
	v_and_b32_e32 v1, 0xffff0000, v1
	v_add_f32_e32 v9, v61, v9
	v_pk_fma_f32 v[68:69], v[74:75], v[68:69], v[0:1]
	v_add_f32_e32 v9, v66, v9
	v_pk_mul_f32 v[0:1], v[68:69], v[68:69]
	v_lshlrev_b32_e32 v70, 16, v2
	v_and_b32_e32 v71, 0xffff0000, v2
	v_add_f32_e32 v9, v67, v9
	s_waitcnt vmcnt(4)
	v_pk_fma_f32 v[4:5], v[48:49], v[4:5], v[70:71]
	v_add_f32_e32 v0, v0, v9
	v_pk_mul_f32 v[48:49], v[4:5], v[4:5]
	v_lshlrev_b32_e32 v2, 16, v3
	v_and_b32_e32 v3, 0xffff0000, v3
	v_add_f32_e32 v0, v1, v0
	v_pk_fma_f32 v[6:7], v[76:77], v[6:7], v[2:3]
	v_add_f32_e32 v0, v48, v0
	v_pk_mul_f32 v[2:3], v[6:7], v[6:7]
	v_add_f32_e32 v0, v49, v0
	v_add_f32_e32 v0, v2, v0
	v_add_f32_e32 v0, v3, v0
	s_nop 1
	v_add_f32_dpp v0, v0, v0 row_ror:8 row_mask:0xf bank_mask:0xf
	s_nop 1
	v_add_f32_dpp v0, v0, v0 row_ror:4 row_mask:0xf bank_mask:0xf
	s_nop 1
	v_add_f32_dpp v0, v0, v0 row_ror:2 row_mask:0xf bank_mask:0xf
	s_nop 1
	v_add_f32_dpp v0, v0, v0 row_ror:1 row_mask:0xf bank_mask:0xf
	v_mov_b32_e32 v1, v0
	s_nop 1
	v_permlane16_swap_b32_e32 v0, v1
	v_add_f32_e32 v0, v0, v1
	v_mov_b32_e32 v1, v0
	s_nop 1
	v_permlane32_swap_b32_e32 v0, v1
	v_add_f32_e32 v0, v0, v1
	v_fmamk_f32 v0, v0, 0x3a800000, v130
	v_mul_f32_e32 v1, 0x4b800000, v0
	v_cmp_gt_f32_e32 vcc, s38, v0
	s_nop 1
	v_cndmask_b32_e32 v0, v0, v1, vcc
	v_rsq_f32_e32 v0, v0
	s_nop 0
	v_mul_f32_e32 v1, 0x45800000, v0
	v_cndmask_b32_e32 v12, v0, v1, vcc
	v_pk_mul_f32 v[0:1], v[28:29], v[12:13] op_sel_hi:[1,0]
	v_pk_mul_f32 v[2:3], v[50:51], v[12:13] op_sel_hi:[1,0]
	s_waitcnt vmcnt(0)
	v_pk_mul_f32 v[0:1], v[44:45], v[0:1]
	v_pk_mul_f32 v[2:3], v[46:47], v[2:3]
	ds_write_b128 v118, v[0:3]
	v_pk_mul_f32 v[0:1], v[52:53], v[12:13] op_sel_hi:[1,0]
	v_pk_mul_f32 v[2:3], v[54:55], v[12:13] op_sel_hi:[1,0]
	v_pk_mul_f32 v[0:1], v[40:41], v[0:1]
	v_pk_mul_f32 v[2:3], v[42:43], v[2:3]
	ds_write_b128 v118, v[0:3] offset:16
	v_pk_mul_f32 v[0:1], v[56:57], v[12:13] op_sel_hi:[1,0]
	v_pk_mul_f32 v[2:3], v[68:69], v[12:13] op_sel_hi:[1,0]
	v_pk_mul_f32 v[0:1], v[36:37], v[0:1]
	v_pk_mul_f32 v[2:3], v[38:39], v[2:3]
	ds_write_b128 v118, v[0:3] offset:32
	v_pk_mul_f32 v[0:1], v[4:5], v[12:13] op_sel_hi:[1,0]
	v_pk_mul_f32 v[2:3], v[6:7], v[12:13] op_sel_hi:[1,0]
	v_pk_mul_f32 v[0:1], v[32:33], v[0:1]
	v_pk_mul_f32 v[2:3], v[34:35], v[2:3]
	ds_write_b128 v118, v[0:3] offset:48
	ds_read_b128 v[0:3], v128
	ds_read_b128 v[4:7], v128 offset:1024
	v_lshlrev_b64 v[32:33], 12, v[30:31]
	v_lshl_add_u64 v[32:33], v[18:19], 0, v[32:33]
	ds_read_b128 v[28:31], v128 offset:2048
	s_waitcnt lgkmcnt(2)
	global_store_dwordx4 v[32:33], v[0:3], off
	s_waitcnt lgkmcnt(1)
	global_store_dwordx4 v[32:33], v[4:7], off offset:1024
	ds_read_b128 v[0:3], v128 offset:3072
	v_cmp_lt_i32_e32 vcc, s41, v8
	s_or_b64 s[28:29], vcc, s[28:29]
	s_waitcnt lgkmcnt(1)
	global_store_dwordx4 v[32:33], v[28:31], off offset:2048
	s_waitcnt lgkmcnt(0)
	global_store_dwordx4 v[32:33], v[0:3], off offset:3072
	s_andn2_b64 exec, exec, s[28:29]
	s_cbranch_execnz .LBB0_1042
